# GEMM tile prologue issues the A tiles of the first two K steps at once
# baseline (speedup 1.0000x reference)
.Lg2_ff2_nodma_0:
	global_load_dwordx4 v[184:187], v160, s[58:59] offset:0
	global_load_dwordx4 v[188:191], v160, s[58:59] offset:1024
	global_load_dwordx4 v[192:195], v161, s[58:59] offset:0
	global_load_dwordx4 v[196:199], v161, s[58:59] offset:1024
	s_add_u32 s56, s56, 0x80
	s_addc_u32 s57, s57, 0
	s_add_u32 m0, s62, 0x8800
	s_add_u32 s4, s56, 0x0
	s_addc_u32 s5, s57, 0
	global_load_lds_dwordx4 v162, s[4:5]
	s_add_u32 m0, s62, 0x9800
	s_add_u32 s4, s56, 0x40000
	s_addc_u32 s5, s57, 0
	global_load_lds_dwordx4 v162, s[4:5]
	s_add_u32 m0, s62, 0xa800
	s_add_u32 s4, s56, 0x80000
	s_addc_u32 s5, s57, 0
	global_load_lds_dwordx4 v162, s[4:5]
	s_add_u32 m0, s62, 0xb800
	s_add_u32 s4, s56, 0xc0000
	s_addc_u32 s5, s57, 0
	global_load_lds_dwordx4 v162, s[4:5]
	s_add_u32 m0, s62, 0xc800
	s_add_u32 s4, s56, 0x100000
	s_addc_u32 s5, s57, 0
	global_load_lds_dwordx4 v162, s[4:5]
	s_add_u32 m0, s62, 0xd800
	s_add_u32 s4, s56, 0x140000
	s_addc_u32 s5, s57, 0
	global_load_lds_dwordx4 v162, s[4:5]
	s_add_u32 m0, s62, 0xe800
	s_add_u32 s4, s56, 0x180000
	s_addc_u32 s5, s57, 0
	global_load_lds_dwordx4 v162, s[4:5]
	s_add_u32 m0, s62, 0xf800
	s_add_u32 s4, s56, 0x1c0000
	s_addc_u32 s5, s57, 0
	global_load_lds_dwordx4 v162, s[4:5]
	s_cmp_gt_u32 s70, 1
	s_cbranch_scc1 .Lg2_ff2_nodma_1
	s_add_u32 m0, s62, 0x10800
	s_add_u32 s4, s56, 0x200000
	s_addc_u32 s5, s57, 0
	global_load_lds_dwordx4 v162, s[4:5]
.Lg2_ff2_nodma_1:
	v_mov_b32_e32 v0, 0
	v_mov_b32_e32 v1, 0
	v_mov_b32_e32 v2, 0
	v_mov_b32_e32 v3, 0
	v_mov_b32_e32 v4, 0
	v_mov_b32_e32 v5, 0
	v_mov_b32_e32 v6, 0
	v_mov_b32_e32 v7, 0
	v_mov_b32_e32 v8, 0
	v_mov_b32_e32 v9, 0
	v_mov_b32_e32 v10, 0
	v_mov_b32_e32 v11, 0
	v_mov_b32_e32 v12, 0
	v_mov_b32_e32 v13, 0
	v_mov_b32_e32 v14, 0
	v_mov_b32_e32 v15, 0
	v_mov_b32_e32 v16, 0
	v_mov_b32_e32 v17, 0
	v_mov_b32_e32 v18, 0
	v_mov_b32_e32 v19, 0
	v_mov_b32_e32 v20, 0
	v_mov_b32_e32 v21, 0
	v_mov_b32_e32 v22, 0
	v_mov_b32_e32 v23, 0
	v_mov_b32_e32 v24, 0
	v_mov_b32_e32 v25, 0
	v_mov_b32_e32 v26, 0
	v_mov_b32_e32 v27, 0
	v_mov_b32_e32 v28, 0
	v_mov_b32_e32 v29, 0
	v_mov_b32_e32 v30, 0
	v_mov_b32_e32 v31, 0
	v_mov_b32_e32 v32, 0
	v_mov_b32_e32 v33, 0
	v_mov_b32_e32 v34, 0
	v_mov_b32_e32 v35, 0
	v_mov_b32_e32 v36, 0
	v_mov_b32_e32 v37, 0
	v_mov_b32_e32 v38, 0
	v_mov_b32_e32 v39, 0
	v_mov_b32_e32 v40, 0
	v_mov_b32_e32 v41, 0
	v_mov_b32_e32 v42, 0
	v_mov_b32_e32 v43, 0
	v_mov_b32_e32 v44, 0
	v_mov_b32_e32 v45, 0
	v_mov_b32_e32 v46, 0
	v_mov_b32_e32 v47, 0
	v_mov_b32_e32 v48, 0
	v_mov_b32_e32 v49, 0
	v_mov_b32_e32 v50, 0
	v_mov_b32_e32 v51, 0
	v_mov_b32_e32 v52, 0
	v_mov_b32_e32 v53, 0
	v_mov_b32_e32 v54, 0
	v_mov_b32_e32 v55, 0
	v_mov_b32_e32 v56, 0
	v_mov_b32_e32 v57, 0
	v_mov_b32_e32 v58, 0
	v_mov_b32_e32 v59, 0
	v_mov_b32_e32 v60, 0
	v_mov_b32_e32 v61, 0
	v_mov_b32_e32 v62, 0
	v_mov_b32_e32 v63, 0
	v_mov_b32_e32 v64, 0
	v_mov_b32_e32 v65, 0
	v_mov_b32_e32 v66, 0
	v_mov_b32_e32 v67, 0
	v_mov_b32_e32 v68, 0
	v_mov_b32_e32 v69, 0
	v_mov_b32_e32 v70, 0
	v_mov_b32_e32 v71, 0
	v_mov_b32_e32 v72, 0
	v_mov_b32_e32 v73, 0
	v_mov_b32_e32 v74, 0
	v_mov_b32_e32 v75, 0
	v_mov_b32_e32 v76, 0
	v_mov_b32_e32 v77, 0
	v_mov_b32_e32 v78, 0
	v_mov_b32_e32 v79, 0
	v_mov_b32_e32 v80, 0
	v_mov_b32_e32 v81, 0
	v_mov_b32_e32 v82, 0
	v_mov_b32_e32 v83, 0
	v_mov_b32_e32 v84, 0
	v_mov_b32_e32 v85, 0
	v_mov_b32_e32 v86, 0
	v_mov_b32_e32 v87, 0
	v_mov_b32_e32 v88, 0
	v_mov_b32_e32 v89, 0
	v_mov_b32_e32 v90, 0
	v_mov_b32_e32 v91, 0
	v_mov_b32_e32 v92, 0
	v_mov_b32_e32 v93, 0
	v_mov_b32_e32 v94, 0
	v_mov_b32_e32 v95, 0
	v_mov_b32_e32 v96, 0
	v_mov_b32_e32 v97, 0
	v_mov_b32_e32 v98, 0
	v_mov_b32_e32 v99, 0
	v_mov_b32_e32 v100, 0
	v_mov_b32_e32 v101, 0
	v_mov_b32_e32 v102, 0
	v_mov_b32_e32 v103, 0
	v_mov_b32_e32 v104, 0
	v_mov_b32_e32 v105, 0
	v_mov_b32_e32 v106, 0
	v_mov_b32_e32 v107, 0
	v_mov_b32_e32 v108, 0
	v_mov_b32_e32 v109, 0
	v_mov_b32_e32 v110, 0
	v_mov_b32_e32 v111, 0
	v_mov_b32_e32 v112, 0
	v_mov_b32_e32 v113, 0
	v_mov_b32_e32 v114, 0
	v_mov_b32_e32 v115, 0
	v_mov_b32_e32 v116, 0
	v_mov_b32_e32 v117, 0
	v_mov_b32_e32 v118, 0
	v_mov_b32_e32 v119, 0
	v_mov_b32_e32 v120, 0
	v_mov_b32_e32 v121, 0
	v_mov_b32_e32 v122, 0
	v_mov_b32_e32 v123, 0
	v_mov_b32_e32 v124, 0
	v_mov_b32_e32 v125, 0
	v_mov_b32_e32 v126, 0
	v_mov_b32_e32 v127, 0
	v_mov_b32_e32 v128, 0
	v_mov_b32_e32 v129, 0
	v_mov_b32_e32 v130, 0
	v_mov_b32_e32 v131, 0
	v_mov_b32_e32 v132, 0
	v_mov_b32_e32 v133, 0
	v_mov_b32_e32 v134, 0
	v_mov_b32_e32 v135, 0
	s_mov_b32 s63, 0
	s_waitcnt vmcnt(0)
	s_barrier
	ds_read_b128 v[136:139], v156 offset:0
	ds_read_b128 v[140:143], v156 offset:2048
	ds_read_b128 v[144:147], v156 offset:4096
	ds_read_b128 v[148:151], v156 offset:6144

.Lg2_ff2_k16:
	s_add_u32 m0, s62, 0x0
	s_add_u32 s4, s56, 0x0
	s_addc_u32 s5, s57, 0
	global_load_lds_dwordx4 v162, s[4:5]
	s_add_u32 m0, s62, 0x1000
	s_add_u32 s4, s56, 0x40000
	s_addc_u32 s5, s57, 0
	global_load_lds_dwordx4 v162, s[4:5]
	s_add_u32 m0, s62, 0x2000
	s_add_u32 s4, s56, 0x80000
	s_addc_u32 s5, s57, 0
	global_load_lds_dwordx4 v162, s[4:5]
	s_add_u32 m0, s62, 0x3000
	s_add_u32 s4, s56, 0xc0000
	s_addc_u32 s5, s57, 0
	global_load_lds_dwordx4 v162, s[4:5]
	s_add_u32 m0, s62, 0x4000
	s_add_u32 s4, s56, 0x100000
	s_addc_u32 s5, s57, 0
	global_load_lds_dwordx4 v162, s[4:5]
	s_add_u32 m0, s62, 0x5000
	s_add_u32 s4, s56, 0x140000
	s_addc_u32 s5, s57, 0
	global_load_lds_dwordx4 v162, s[4:5]
	s_add_u32 m0, s62, 0x6000
	s_add_u32 s4, s56, 0x180000
	s_addc_u32 s5, s57, 0
	global_load_lds_dwordx4 v162, s[4:5]
	s_add_u32 m0, s62, 0x7000
	s_add_u32 s4, s56, 0x1c0000
	s_addc_u32 s5, s57, 0
	global_load_lds_dwordx4 v162, s[4:5]
	global_load_dwordx4 v[184:187], v160, s[58:59] offset:0
	global_load_dwordx4 v[188:191], v160, s[58:59] offset:1024
	global_load_dwordx4 v[192:195], v161, s[58:59] offset:0
	global_load_dwordx4 v[196:199], v161, s[58:59] offset:1024
	s_add_u32 s56, s56, 0x80
	s_addc_u32 s57, s57, 0
	s_add_u32 m0, s62, 0x8800
	s_add_u32 s4, s56, 0x0
	s_addc_u32 s5, s57, 0
	global_load_lds_dwordx4 v162, s[4:5]
	s_add_u32 m0, s62, 0x9800
	s_add_u32 s4, s56, 0x40000
	s_addc_u32 s5, s57, 0
	global_load_lds_dwordx4 v162, s[4:5]
	s_add_u32 m0, s62, 0xa800
	s_add_u32 s4, s56, 0x80000
	s_addc_u32 s5, s57, 0
	global_load_lds_dwordx4 v162, s[4:5]
	s_add_u32 m0, s62, 0xb800
	s_add_u32 s4, s56, 0xc0000
	s_addc_u32 s5, s57, 0
	global_load_lds_dwordx4 v162, s[4:5]
	s_add_u32 m0, s62, 0xc800
	s_add_u32 s4, s56, 0x100000
	s_addc_u32 s5, s57, 0
	global_load_lds_dwordx4 v162, s[4:5]
	s_add_u32 m0, s62, 0xd800
	s_add_u32 s4, s56, 0x140000
	s_addc_u32 s5, s57, 0
	global_load_lds_dwordx4 v162, s[4:5]
	s_add_u32 m0, s62, 0xe800
	s_add_u32 s4, s56, 0x180000
	s_addc_u32 s5, s57, 0
	global_load_lds_dwordx4 v162, s[4:5]
	s_add_u32 m0, s62, 0xf800
	s_add_u32 s4, s56, 0x1c0000
	s_addc_u32 s5, s57, 0
	global_load_lds_dwordx4 v162, s[4:5]
	v_mov_b32_e32 v0, 0
	v_mov_b32_e32 v1, 0
	v_mov_b32_e32 v2, 0
	v_mov_b32_e32 v3, 0
	v_mov_b32_e32 v4, 0
	v_mov_b32_e32 v5, 0
	v_mov_b32_e32 v6, 0
	v_mov_b32_e32 v7, 0
	v_mov_b32_e32 v8, 0
	v_mov_b32_e32 v9, 0
	v_mov_b32_e32 v10, 0
	v_mov_b32_e32 v11, 0
	v_mov_b32_e32 v12, 0
	v_mov_b32_e32 v13, 0
	v_mov_b32_e32 v14, 0
	v_mov_b32_e32 v15, 0
	v_mov_b32_e32 v16, 0
	v_mov_b32_e32 v17, 0
	v_mov_b32_e32 v18, 0
	v_mov_b32_e32 v19, 0
	v_mov_b32_e32 v20, 0
	v_mov_b32_e32 v21, 0
	v_mov_b32_e32 v22, 0
	v_mov_b32_e32 v23, 0
	v_mov_b32_e32 v24, 0
	v_mov_b32_e32 v25, 0
	v_mov_b32_e32 v26, 0
	v_mov_b32_e32 v27, 0
	v_mov_b32_e32 v28, 0
	v_mov_b32_e32 v29, 0
	v_mov_b32_e32 v30, 0
	v_mov_b32_e32 v31, 0
	v_mov_b32_e32 v32, 0
	v_mov_b32_e32 v33, 0
	v_mov_b32_e32 v34, 0
	v_mov_b32_e32 v35, 0
	v_mov_b32_e32 v36, 0
	v_mov_b32_e32 v37, 0
	v_mov_b32_e32 v38, 0
	v_mov_b32_e32 v39, 0
	v_mov_b32_e32 v40, 0
	v_mov_b32_e32 v41, 0
	v_mov_b32_e32 v42, 0
	v_mov_b32_e32 v43, 0
	v_mov_b32_e32 v44, 0
	v_mov_b32_e32 v45, 0
	v_mov_b32_e32 v46, 0
	v_mov_b32_e32 v47, 0
	v_mov_b32_e32 v48, 0
	v_mov_b32_e32 v49, 0
	v_mov_b32_e32 v50, 0
	v_mov_b32_e32 v51, 0
	v_mov_b32_e32 v52, 0
	v_mov_b32_e32 v53, 0
	v_mov_b32_e32 v54, 0
	v_mov_b32_e32 v55, 0
	v_mov_b32_e32 v56, 0
	v_mov_b32_e32 v57, 0
	v_mov_b32_e32 v58, 0
	v_mov_b32_e32 v59, 0
	v_mov_b32_e32 v60, 0
	v_mov_b32_e32 v61, 0
	v_mov_b32_e32 v62, 0
	v_mov_b32_e32 v63, 0
	v_mov_b32_e32 v64, 0
	v_mov_b32_e32 v65, 0
	v_mov_b32_e32 v66, 0
	v_mov_b32_e32 v67, 0
	v_mov_b32_e32 v68, 0
	v_mov_b32_e32 v69, 0
	v_mov_b32_e32 v70, 0
	v_mov_b32_e32 v71, 0
	v_mov_b32_e32 v72, 0
	v_mov_b32_e32 v73, 0
	v_mov_b32_e32 v74, 0
	v_mov_b32_e32 v75, 0
	v_mov_b32_e32 v76, 0
	v_mov_b32_e32 v77, 0
	v_mov_b32_e32 v78, 0
	v_mov_b32_e32 v79, 0
	v_mov_b32_e32 v80, 0
	v_mov_b32_e32 v81, 0
	v_mov_b32_e32 v82, 0
	v_mov_b32_e32 v83, 0
	v_mov_b32_e32 v84, 0
	v_mov_b32_e32 v85, 0
	v_mov_b32_e32 v86, 0
	v_mov_b32_e32 v87, 0
	v_mov_b32_e32 v88, 0
	v_mov_b32_e32 v89, 0
	v_mov_b32_e32 v90, 0
	v_mov_b32_e32 v91, 0
	v_mov_b32_e32 v92, 0
	v_mov_b32_e32 v93, 0
	v_mov_b32_e32 v94, 0
	v_mov_b32_e32 v95, 0
	v_mov_b32_e32 v96, 0
	v_mov_b32_e32 v97, 0
	v_mov_b32_e32 v98, 0
	v_mov_b32_e32 v99, 0
	v_mov_b32_e32 v100, 0
	v_mov_b32_e32 v101, 0
	v_mov_b32_e32 v102, 0
	v_mov_b32_e32 v103, 0
	v_mov_b32_e32 v104, 0
	v_mov_b32_e32 v105, 0
	v_mov_b32_e32 v106, 0
	v_mov_b32_e32 v107, 0
	v_mov_b32_e32 v108, 0
	v_mov_b32_e32 v109, 0
	v_mov_b32_e32 v110, 0
	v_mov_b32_e32 v111, 0
	v_mov_b32_e32 v112, 0
	v_mov_b32_e32 v113, 0
	v_mov_b32_e32 v114, 0
	v_mov_b32_e32 v115, 0
	v_mov_b32_e32 v116, 0
	v_mov_b32_e32 v117, 0
	v_mov_b32_e32 v118, 0
	v_mov_b32_e32 v119, 0
	v_mov_b32_e32 v120, 0
	v_mov_b32_e32 v121, 0
	v_mov_b32_e32 v122, 0
	v_mov_b32_e32 v123, 0
	v_mov_b32_e32 v124, 0
	v_mov_b32_e32 v125, 0
	v_mov_b32_e32 v126, 0
	v_mov_b32_e32 v127, 0
	s_mov_b32 s63, 0
	s_waitcnt vmcnt(0)
	s_barrier
	ds_read_b128 v[136:139], v156 offset:0
	ds_read_b128 v[140:143], v156 offset:2048
	ds_read_b128 v[144:147], v156 offset:4096
	ds_read_b128 v[148:151], v156 offset:6144

.Lg2_ff1_nodma_0:
	global_load_dwordx4 v[184:187], v160, s[58:59] offset:0
	global_load_dwordx4 v[188:191], v160, s[58:59] offset:1024
	global_load_dwordx4 v[192:195], v161, s[58:59] offset:0
	global_load_dwordx4 v[196:199], v161, s[58:59] offset:1024
	s_add_u32 s56, s56, 0x80
	s_addc_u32 s57, s57, 0
	s_add_u32 m0, s62, 0x8800
	s_add_u32 s4, s56, 0x0
	s_addc_u32 s5, s57, 0
	global_load_lds_dwordx4 v162, s[4:5]
	s_add_u32 m0, s62, 0x9800
	s_add_u32 s4, s56, 0x10000
	s_addc_u32 s5, s57, 0
	global_load_lds_dwordx4 v162, s[4:5]
	s_add_u32 m0, s62, 0xa800
	s_add_u32 s4, s56, 0x20000
	s_addc_u32 s5, s57, 0
	global_load_lds_dwordx4 v162, s[4:5]
	s_add_u32 m0, s62, 0xb800
	s_add_u32 s4, s56, 0x30000
	s_addc_u32 s5, s57, 0
	global_load_lds_dwordx4 v162, s[4:5]
	s_add_u32 m0, s62, 0xc800
	s_add_u32 s4, s56, 0x40000
	s_addc_u32 s5, s57, 0
	global_load_lds_dwordx4 v162, s[4:5]
	s_add_u32 m0, s62, 0xd800
	s_add_u32 s4, s56, 0x50000
	s_addc_u32 s5, s57, 0
	global_load_lds_dwordx4 v162, s[4:5]
	s_add_u32 m0, s62, 0xe800
	s_add_u32 s4, s56, 0x60000
	s_addc_u32 s5, s57, 0
	global_load_lds_dwordx4 v162, s[4:5]
	s_add_u32 m0, s62, 0xf800
	s_add_u32 s4, s56, 0x70000
	s_addc_u32 s5, s57, 0
	global_load_lds_dwordx4 v162, s[4:5]
	s_cmp_gt_u32 s70, 1
	s_cbranch_scc1 .Lg2_ff1_nodma_1
	s_add_u32 m0, s62, 0x10800
	s_add_u32 s4, s56, 0x80000
	s_addc_u32 s5, s57, 0
	global_load_lds_dwordx4 v162, s[4:5]

.Lg2_ff1_k16:
	s_add_u32 m0, s62, 0x0
	s_add_u32 s4, s56, 0x0
	s_addc_u32 s5, s57, 0
	global_load_lds_dwordx4 v162, s[4:5]
	s_add_u32 m0, s62, 0x1000
	s_add_u32 s4, s56, 0x10000
	s_addc_u32 s5, s57, 0
	global_load_lds_dwordx4 v162, s[4:5]
	s_add_u32 m0, s62, 0x2000
	s_add_u32 s4, s56, 0x20000
	s_addc_u32 s5, s57, 0
	global_load_lds_dwordx4 v162, s[4:5]
	s_add_u32 m0, s62, 0x3000
	s_add_u32 s4, s56, 0x30000
	s_addc_u32 s5, s57, 0
	global_load_lds_dwordx4 v162, s[4:5]
	s_add_u32 m0, s62, 0x4000
	s_add_u32 s4, s56, 0x40000
	s_addc_u32 s5, s57, 0
	global_load_lds_dwordx4 v162, s[4:5]
	s_add_u32 m0, s62, 0x5000
	s_add_u32 s4, s56, 0x50000
	s_addc_u32 s5, s57, 0
	global_load_lds_dwordx4 v162, s[4:5]
	s_add_u32 m0, s62, 0x6000
	s_add_u32 s4, s56, 0x60000
	s_addc_u32 s5, s57, 0
	global_load_lds_dwordx4 v162, s[4:5]
	s_add_u32 m0, s62, 0x7000
	s_add_u32 s4, s56, 0x70000
	s_addc_u32 s5, s57, 0
	global_load_lds_dwordx4 v162, s[4:5]
	global_load_dwordx4 v[184:187], v160, s[58:59] offset:0
	global_load_dwordx4 v[188:191], v160, s[58:59] offset:1024
	global_load_dwordx4 v[192:195], v161, s[58:59] offset:0
	global_load_dwordx4 v[196:199], v161, s[58:59] offset:1024
	s_add_u32 s56, s56, 0x80
	s_addc_u32 s57, s57, 0
	s_add_u32 m0, s62, 0x8800
	s_add_u32 s4, s56, 0x0
	s_addc_u32 s5, s57, 0
	global_load_lds_dwordx4 v162, s[4:5]
	s_add_u32 m0, s62, 0x9800
	s_add_u32 s4, s56, 0x10000
	s_addc_u32 s5, s57, 0
	global_load_lds_dwordx4 v162, s[4:5]
	s_add_u32 m0, s62, 0xa800
	s_add_u32 s4, s56, 0x20000
	s_addc_u32 s5, s57, 0
	global_load_lds_dwordx4 v162, s[4:5]
	s_add_u32 m0, s62, 0xb800
	s_add_u32 s4, s56, 0x30000
	s_addc_u32 s5, s57, 0
	global_load_lds_dwordx4 v162, s[4:5]
	s_add_u32 m0, s62, 0xc800
	s_add_u32 s4, s56, 0x40000
	s_addc_u32 s5, s57, 0
	global_load_lds_dwordx4 v162, s[4:5]
	s_add_u32 m0, s62, 0xd800
	s_add_u32 s4, s56, 0x50000
	s_addc_u32 s5, s57, 0
	global_load_lds_dwordx4 v162, s[4:5]
	s_add_u32 m0, s62, 0xe800
	s_add_u32 s4, s56, 0x60000
	s_addc_u32 s5, s57, 0
	global_load_lds_dwordx4 v162, s[4:5]
	s_add_u32 m0, s62, 0xf800
	s_add_u32 s4, s56, 0x70000
	s_addc_u32 s5, s57, 0
	global_load_lds_dwordx4 v162, s[4:5]
	v_mov_b32_e32 v0, 0
	v_mov_b32_e32 v1, 0
	v_mov_b32_e32 v2, 0
	v_mov_b32_e32 v3, 0
	v_mov_b32_e32 v4, 0
	v_mov_b32_e32 v5, 0
	v_mov_b32_e32 v6, 0
	v_mov_b32_e32 v7, 0
	v_mov_b32_e32 v8, 0
	v_mov_b32_e32 v9, 0
	v_mov_b32_e32 v10, 0
	v_mov_b32_e32 v11, 0
	v_mov_b32_e32 v12, 0
	v_mov_b32_e32 v13, 0
	v_mov_b32_e32 v14, 0
	v_mov_b32_e32 v15, 0
	v_mov_b32_e32 v16, 0
	v_mov_b32_e32 v17, 0
	v_mov_b32_e32 v18, 0
	v_mov_b32_e32 v19, 0
	v_mov_b32_e32 v20, 0
	v_mov_b32_e32 v21, 0
	v_mov_b32_e32 v22, 0
	v_mov_b32_e32 v23, 0
	v_mov_b32_e32 v24, 0
	v_mov_b32_e32 v25, 0
	v_mov_b32_e32 v26, 0
	v_mov_b32_e32 v27, 0
	v_mov_b32_e32 v28, 0
	v_mov_b32_e32 v29, 0
	v_mov_b32_e32 v30, 0
	v_mov_b32_e32 v31, 0
	v_mov_b32_e32 v32, 0
	v_mov_b32_e32 v33, 0
	v_mov_b32_e32 v34, 0
	v_mov_b32_e32 v35, 0
	v_mov_b32_e32 v36, 0
	v_mov_b32_e32 v37, 0
	v_mov_b32_e32 v38, 0
	v_mov_b32_e32 v39, 0
	v_mov_b32_e32 v40, 0
	v_mov_b32_e32 v41, 0
	v_mov_b32_e32 v42, 0
	v_mov_b32_e32 v43, 0
	v_mov_b32_e32 v44, 0
	v_mov_b32_e32 v45, 0
	v_mov_b32_e32 v46, 0
	v_mov_b32_e32 v47, 0
	v_mov_b32_e32 v48, 0
	v_mov_b32_e32 v49, 0
	v_mov_b32_e32 v50, 0
	v_mov_b32_e32 v51, 0
	v_mov_b32_e32 v52, 0
	v_mov_b32_e32 v53, 0
	v_mov_b32_e32 v54, 0
	v_mov_b32_e32 v55, 0
	v_mov_b32_e32 v56, 0
	v_mov_b32_e32 v57, 0
	v_mov_b32_e32 v58, 0
	v_mov_b32_e32 v59, 0
	v_mov_b32_e32 v60, 0
	v_mov_b32_e32 v61, 0
	v_mov_b32_e32 v62, 0
	v_mov_b32_e32 v63, 0
	v_mov_b32_e32 v64, 0
	v_mov_b32_e32 v65, 0
	v_mov_b32_e32 v66, 0
	v_mov_b32_e32 v67, 0
	v_mov_b32_e32 v68, 0
	v_mov_b32_e32 v69, 0
	v_mov_b32_e32 v70, 0
	v_mov_b32_e32 v71, 0
	v_mov_b32_e32 v72, 0
	v_mov_b32_e32 v73, 0
	v_mov_b32_e32 v74, 0
	v_mov_b32_e32 v75, 0
	v_mov_b32_e32 v76, 0
	v_mov_b32_e32 v77, 0
	v_mov_b32_e32 v78, 0
	v_mov_b32_e32 v79, 0
	v_mov_b32_e32 v80, 0
	v_mov_b32_e32 v81, 0
	v_mov_b32_e32 v82, 0
	v_mov_b32_e32 v83, 0
	v_mov_b32_e32 v84, 0
	v_mov_b32_e32 v85, 0
	v_mov_b32_e32 v86, 0
	v_mov_b32_e32 v87, 0
	v_mov_b32_e32 v88, 0
	v_mov_b32_e32 v89, 0
	v_mov_b32_e32 v90, 0
	v_mov_b32_e32 v91, 0
	v_mov_b32_e32 v92, 0
	v_mov_b32_e32 v93, 0
	v_mov_b32_e32 v94, 0
	v_mov_b32_e32 v95, 0
	v_mov_b32_e32 v96, 0
	v_mov_b32_e32 v97, 0
	v_mov_b32_e32 v98, 0
	v_mov_b32_e32 v99, 0
	v_mov_b32_e32 v100, 0
	v_mov_b32_e32 v101, 0
	v_mov_b32_e32 v102, 0
	v_mov_b32_e32 v103, 0
	v_mov_b32_e32 v104, 0
	v_mov_b32_e32 v105, 0
	v_mov_b32_e32 v106, 0
	v_mov_b32_e32 v107, 0
	v_mov_b32_e32 v108, 0
	v_mov_b32_e32 v109, 0
	v_mov_b32_e32 v110, 0
	v_mov_b32_e32 v111, 0
	v_mov_b32_e32 v112, 0
	v_mov_b32_e32 v113, 0
	v_mov_b32_e32 v114, 0
	v_mov_b32_e32 v115, 0
	v_mov_b32_e32 v116, 0
	v_mov_b32_e32 v117, 0
	v_mov_b32_e32 v118, 0
	v_mov_b32_e32 v119, 0
	v_mov_b32_e32 v120, 0
	v_mov_b32_e32 v121, 0
	v_mov_b32_e32 v122, 0
	v_mov_b32_e32 v123, 0
	v_mov_b32_e32 v124, 0
	v_mov_b32_e32 v125, 0
	v_mov_b32_e32 v126, 0
	v_mov_b32_e32 v127, 0
	s_mov_b32 s63, 0
	s_waitcnt vmcnt(0)
	s_barrier
	ds_read_b128 v[136:139], v156 offset:0
	ds_read_b128 v[140:143], v156 offset:2048
	ds_read_b128 v[144:147], v156 offset:4096
	ds_read_b128 v[148:151], v156 offset:6144

.Lg2_up_nodma_0:
	global_load_dwordx4 v[184:187], v160, s[58:59] offset:0
	global_load_dwordx4 v[188:191], v160, s[58:59] offset:1024
	global_load_dwordx4 v[192:195], v161, s[58:59] offset:0
	global_load_dwordx4 v[196:199], v161, s[58:59] offset:1024
	s_add_u32 s56, s56, 0x80
	s_addc_u32 s57, s57, 0
	s_add_u32 m0, s62, 0x8800
	s_add_u32 s4, s56, 0x0
	s_addc_u32 s5, s57, 0
	global_load_lds_dwordx4 v162, s[4:5]
	s_add_u32 m0, s62, 0x9800
	s_add_u32 s4, s56, 0x72000
	s_addc_u32 s5, s57, 0
	global_load_lds_dwordx4 v162, s[4:5]
	s_add_u32 m0, s62, 0xa800
	s_add_u32 s4, s56, 0xe4000
	s_addc_u32 s5, s57, 0
	global_load_lds_dwordx4 v162, s[4:5]
	s_add_u32 m0, s62, 0xb800
	s_add_u32 s4, s56, 0x156000
	s_addc_u32 s5, s57, 0
	global_load_lds_dwordx4 v162, s[4:5]
	s_add_u32 m0, s62, 0xc800
	s_add_u32 s4, s56, 0x1c8000
	s_addc_u32 s5, s57, 0
	global_load_lds_dwordx4 v162, s[4:5]
	s_add_u32 m0, s62, 0xd800
	s_add_u32 s4, s56, 0x23a000
	s_addc_u32 s5, s57, 0
	global_load_lds_dwordx4 v162, s[4:5]
	s_add_u32 m0, s62, 0xe800
	s_add_u32 s4, s56, 0x2ac000
	s_addc_u32 s5, s57, 0
	global_load_lds_dwordx4 v162, s[4:5]
	s_add_u32 m0, s62, 0xf800
	s_add_u32 s4, s56, 0x31e000
	s_addc_u32 s5, s57, 0
	global_load_lds_dwordx4 v162, s[4:5]
	s_cmp_gt_u32 s70, 1
	s_cbranch_scc1 .Lg2_up_nodma_1
	s_add_u32 m0, s62, 0x10800
	s_add_u32 s4, s56, 0x390000
	s_addc_u32 s5, s57, 0
	global_load_lds_dwordx4 v162, s[4:5]

.Lg2_up_k16:
	s_add_u32 m0, s62, 0x0
	s_add_u32 s4, s56, 0x0
	s_addc_u32 s5, s57, 0
	global_load_lds_dwordx4 v162, s[4:5]
	s_add_u32 m0, s62, 0x1000
	s_add_u32 s4, s56, 0x72000
	s_addc_u32 s5, s57, 0
	global_load_lds_dwordx4 v162, s[4:5]
	s_add_u32 m0, s62, 0x2000
	s_add_u32 s4, s56, 0xe4000
	s_addc_u32 s5, s57, 0
	global_load_lds_dwordx4 v162, s[4:5]
	s_add_u32 m0, s62, 0x3000
	s_add_u32 s4, s56, 0x156000
	s_addc_u32 s5, s57, 0
	global_load_lds_dwordx4 v162, s[4:5]
	s_add_u32 m0, s62, 0x4000
	s_add_u32 s4, s56, 0x1c8000
	s_addc_u32 s5, s57, 0
	global_load_lds_dwordx4 v162, s[4:5]
	s_add_u32 m0, s62, 0x5000
	s_add_u32 s4, s56, 0x23a000
	s_addc_u32 s5, s57, 0
	global_load_lds_dwordx4 v162, s[4:5]
	s_add_u32 m0, s62, 0x6000
	s_add_u32 s4, s56, 0x2ac000
	s_addc_u32 s5, s57, 0
	global_load_lds_dwordx4 v162, s[4:5]
	s_add_u32 m0, s62, 0x7000
	s_add_u32 s4, s56, 0x31e000
	s_addc_u32 s5, s57, 0
	global_load_lds_dwordx4 v162, s[4:5]
	global_load_dwordx4 v[184:187], v160, s[58:59] offset:0
	global_load_dwordx4 v[188:191], v160, s[58:59] offset:1024
	global_load_dwordx4 v[192:195], v161, s[58:59] offset:0
	global_load_dwordx4 v[196:199], v161, s[58:59] offset:1024
	s_add_u32 s56, s56, 0x80
	s_addc_u32 s57, s57, 0
	s_add_u32 m0, s62, 0x8800
	s_add_u32 s4, s56, 0x0
	s_addc_u32 s5, s57, 0
	global_load_lds_dwordx4 v162, s[4:5]
	s_add_u32 m0, s62, 0x9800
	s_add_u32 s4, s56, 0x72000
	s_addc_u32 s5, s57, 0
	global_load_lds_dwordx4 v162, s[4:5]
	s_add_u32 m0, s62, 0xa800
	s_add_u32 s4, s56, 0xe4000
	s_addc_u32 s5, s57, 0
	global_load_lds_dwordx4 v162, s[4:5]
	s_add_u32 m0, s62, 0xb800
	s_add_u32 s4, s56, 0x156000
	s_addc_u32 s5, s57, 0
	global_load_lds_dwordx4 v162, s[4:5]
	s_add_u32 m0, s62, 0xc800
	s_add_u32 s4, s56, 0x1c8000
	s_addc_u32 s5, s57, 0
	global_load_lds_dwordx4 v162, s[4:5]
	s_add_u32 m0, s62, 0xd800
	s_add_u32 s4, s56, 0x23a000
	s_addc_u32 s5, s57, 0
	global_load_lds_dwordx4 v162, s[4:5]
	s_add_u32 m0, s62, 0xe800
	s_add_u32 s4, s56, 0x2ac000
	s_addc_u32 s5, s57, 0
	global_load_lds_dwordx4 v162, s[4:5]
	s_add_u32 m0, s62, 0xf800
	s_add_u32 s4, s56, 0x31e000
	s_addc_u32 s5, s57, 0
	global_load_lds_dwordx4 v162, s[4:5]
	v_mov_b32_e32 v0, 0
	v_mov_b32_e32 v1, 0
	v_mov_b32_e32 v2, 0
	v_mov_b32_e32 v3, 0
	v_mov_b32_e32 v4, 0
	v_mov_b32_e32 v5, 0
	v_mov_b32_e32 v6, 0
	v_mov_b32_e32 v7, 0
	v_mov_b32_e32 v8, 0
	v_mov_b32_e32 v9, 0
	v_mov_b32_e32 v10, 0
	v_mov_b32_e32 v11, 0
	v_mov_b32_e32 v12, 0
	v_mov_b32_e32 v13, 0
	v_mov_b32_e32 v14, 0
	v_mov_b32_e32 v15, 0
	v_mov_b32_e32 v16, 0
	v_mov_b32_e32 v17, 0
	v_mov_b32_e32 v18, 0
	v_mov_b32_e32 v19, 0
	v_mov_b32_e32 v20, 0
	v_mov_b32_e32 v21, 0
	v_mov_b32_e32 v22, 0
	v_mov_b32_e32 v23, 0
	v_mov_b32_e32 v24, 0
	v_mov_b32_e32 v25, 0
	v_mov_b32_e32 v26, 0
	v_mov_b32_e32 v27, 0
	v_mov_b32_e32 v28, 0
	v_mov_b32_e32 v29, 0
	v_mov_b32_e32 v30, 0
	v_mov_b32_e32 v31, 0
	v_mov_b32_e32 v32, 0
	v_mov_b32_e32 v33, 0
	v_mov_b32_e32 v34, 0
	v_mov_b32_e32 v35, 0
	v_mov_b32_e32 v36, 0
	v_mov_b32_e32 v37, 0
	v_mov_b32_e32 v38, 0
	v_mov_b32_e32 v39, 0
	v_mov_b32_e32 v40, 0
	v_mov_b32_e32 v41, 0
	v_mov_b32_e32 v42, 0
	v_mov_b32_e32 v43, 0
	v_mov_b32_e32 v44, 0
	v_mov_b32_e32 v45, 0
	v_mov_b32_e32 v46, 0
	v_mov_b32_e32 v47, 0
	v_mov_b32_e32 v48, 0
	v_mov_b32_e32 v49, 0
	v_mov_b32_e32 v50, 0
	v_mov_b32_e32 v51, 0
	v_mov_b32_e32 v52, 0
	v_mov_b32_e32 v53, 0
	v_mov_b32_e32 v54, 0
	v_mov_b32_e32 v55, 0
	v_mov_b32_e32 v56, 0
	v_mov_b32_e32 v57, 0
	v_mov_b32_e32 v58, 0
	v_mov_b32_e32 v59, 0
	v_mov_b32_e32 v60, 0
	v_mov_b32_e32 v61, 0
	v_mov_b32_e32 v62, 0
	v_mov_b32_e32 v63, 0
	v_mov_b32_e32 v64, 0
	v_mov_b32_e32 v65, 0
	v_mov_b32_e32 v66, 0
	v_mov_b32_e32 v67, 0
	v_mov_b32_e32 v68, 0
	v_mov_b32_e32 v69, 0
	v_mov_b32_e32 v70, 0
	v_mov_b32_e32 v71, 0
	v_mov_b32_e32 v72, 0
	v_mov_b32_e32 v73, 0
	v_mov_b32_e32 v74, 0
	v_mov_b32_e32 v75, 0
	v_mov_b32_e32 v76, 0
	v_mov_b32_e32 v77, 0
	v_mov_b32_e32 v78, 0
	v_mov_b32_e32 v79, 0
	v_mov_b32_e32 v80, 0
	v_mov_b32_e32 v81, 0
	v_mov_b32_e32 v82, 0
	v_mov_b32_e32 v83, 0
	v_mov_b32_e32 v84, 0
	v_mov_b32_e32 v85, 0
	v_mov_b32_e32 v86, 0
	v_mov_b32_e32 v87, 0
	v_mov_b32_e32 v88, 0
	v_mov_b32_e32 v89, 0
	v_mov_b32_e32 v90, 0
	v_mov_b32_e32 v91, 0
	v_mov_b32_e32 v92, 0
	v_mov_b32_e32 v93, 0
	v_mov_b32_e32 v94, 0
	v_mov_b32_e32 v95, 0
	v_mov_b32_e32 v96, 0
	v_mov_b32_e32 v97, 0
	v_mov_b32_e32 v98, 0
	v_mov_b32_e32 v99, 0
	v_mov_b32_e32 v100, 0
	v_mov_b32_e32 v101, 0
	v_mov_b32_e32 v102, 0
	v_mov_b32_e32 v103, 0
	v_mov_b32_e32 v104, 0
	v_mov_b32_e32 v105, 0
	v_mov_b32_e32 v106, 0
	v_mov_b32_e32 v107, 0
	v_mov_b32_e32 v108, 0
	v_mov_b32_e32 v109, 0
	v_mov_b32_e32 v110, 0
	v_mov_b32_e32 v111, 0
	v_mov_b32_e32 v112, 0
	v_mov_b32_e32 v113, 0
	v_mov_b32_e32 v114, 0
	v_mov_b32_e32 v115, 0
	v_mov_b32_e32 v116, 0
	v_mov_b32_e32 v117, 0
	v_mov_b32_e32 v118, 0
	v_mov_b32_e32 v119, 0
	v_mov_b32_e32 v120, 0
	v_mov_b32_e32 v121, 0
	v_mov_b32_e32 v122, 0
	v_mov_b32_e32 v123, 0
	v_mov_b32_e32 v124, 0
	v_mov_b32_e32 v125, 0
	v_mov_b32_e32 v126, 0
	v_mov_b32_e32 v127, 0
	s_mov_b32 s63, 0
	s_waitcnt vmcnt(0)
	s_barrier
	ds_read_b128 v[136:139], v156 offset:0
	ds_read_b128 v[140:143], v156 offset:2048
	ds_read_b128 v[144:147], v156 offset:4096
	ds_read_b128 v[148:151], v156 offset:6144
